# prep conversion loop + hand-written FFN residual/norm epilogue with batched loads
# baseline (speedup 1.0000x reference)
.LBB0_1333:
	s_waitcnt vmcnt(0) lgkmcnt(0)
	v_readlane_b32 s20, v255, 36
	v_and_b32_e32 v130, 31, v189
	v_bfe_u32 v131, v189, 5, 1
	v_lshrrev_b32_e32 v132, 6, v189
	v_lshrrev_b32_e32 v133, 2, v132
	v_and_b32_e32 v134, 3, v132
	s_lshr_b32 s100, s73, 7
	s_lshl_b32 s100, s100, 5
	s_and_b32 s101, s73, 31
	s_add_u32 s70, s100, s101
	s_bfe_u32 s76, s73, 0x20005
	s_lshl_b32 s71, s70, 8
	s_lshl_b32 s76, s76, 8
	v_lshl_add_u32 v135, v133, 7, v130
	v_add_u32_e32 v135, s71, v135
	v_lshlrev_b32_e32 v136, 6, v134
	v_lshl_add_u32 v136, v131, 2, v136
	v_add_u32_e32 v136, s76, v136
	s_sub_u32 s100, s71, 0x2000
	s_lshr_b32 s100, s100, 11
	s_cmp_lt_u32 s71, 0x2000
	s_cselect_b32 s77, 4, s100
	v_mov_b32_e32 v191, 0
	v_lshlrev_b32_e32 v192, 2, v136
	v_lshl_add_u32 v192, v135, 12, v192
	s_load_dwordx2 s[10:11], s[0:1], 0xd8
	s_mov_b32 s101, 0x20000
	s_waitcnt lgkmcnt(0)
	v_mov_b32_e32 v190, v192
	v_lshl_add_u64 v[174:175], v[190:191], 0, s[10:11]
	v_add_u32_e32 v190, s101, v190
	v_lshl_add_u64 v[176:177], v[190:191], 0, s[10:11]
	v_add_u32_e32 v190, s101, v190
	v_lshl_add_u64 v[178:179], v[190:191], 0, s[10:11]
	v_add_u32_e32 v190, s101, v190
	v_lshl_add_u64 v[180:181], v[190:191], 0, s[10:11]
	s_load_dwordx2 s[10:11], s[0:1], 0xe0
	s_mul_i32 s100, s20, 5
	s_add_u32 s100, s100, s77
	s_mul_i32 s100, s100, 0x6000
	s_add_u32 s100, s100, 0x5000
	v_and_b32_e32 v190, 0xfff, v192
	v_add_u32_e32 v190, s100, v190
	s_waitcnt lgkmcnt(0)
	v_lshl_add_u64 v[182:183], v[190:191], 0, s[10:11]
	s_lshl_b32 s100, s20, 1
	s_add_u32 s100, s100, 1
	s_lshl_b32 s100, s100, 16
	s_add_u32 s100, s100, 0x15644000
	v_lshrrev_b32_e32 v190, 12, v192
	v_lshl_add_u32 v190, v190, 2, s100
	v_lshl_add_u64 v[184:185], v[190:191], 0, s[10:11]
	s_cmp_eq_u32 s20, 3
	s_cbranch_scc1 .Lrs_ffn_final
	global_load_dwordx4 v[130:133], v[182:183], off offset:0
	global_load_dwordx4 v[134:137], v[182:183], off offset:32
	global_load_dwordx4 v[138:141], v[174:175], off offset:0
	global_load_dwordx4 v[142:145], v[174:175], off offset:32
	global_load_dwordx4 v[146:149], v[176:177], off offset:0
	global_load_dwordx4 v[150:153], v[176:177], off offset:32
	global_load_dwordx4 v[154:157], v[178:179], off offset:0
	global_load_dwordx4 v[158:161], v[178:179], off offset:32
	global_load_dwordx4 v[162:165], v[180:181], off offset:0
	global_load_dwordx4 v[166:169], v[180:181], off offset:32
	s_waitcnt vmcnt(7)
	v_pk_fma_f32 v[114:115], v[114:115], v[130:131], v[138:139]
	v_pk_fma_f32 v[116:117], v[116:117], v[132:133], v[140:141]
	global_store_dwordx4 v[174:175], v[114:117], off offset:0
	v_mul_f32_e32 v170, v114, v114
	v_fmac_f32_e32 v170, v115, v115
	v_fmac_f32_e32 v170, v116, v116
	v_fmac_f32_e32 v170, v117, v117
	s_waitcnt vmcnt(7)
	v_pk_fma_f32 v[118:119], v[118:119], v[134:135], v[142:143]
	v_pk_fma_f32 v[120:121], v[120:121], v[136:137], v[144:145]
	global_store_dwordx4 v[174:175], v[118:121], off offset:32
	v_fmac_f32_e32 v170, v118, v118
	v_fmac_f32_e32 v170, v119, v119
	v_fmac_f32_e32 v170, v120, v120
	v_fmac_f32_e32 v170, v121, v121
	s_waitcnt vmcnt(7)
	v_pk_fma_f32 v[82:83], v[82:83], v[130:131], v[146:147]
	v_pk_fma_f32 v[84:85], v[84:85], v[132:133], v[148:149]
	global_store_dwordx4 v[176:177], v[82:85], off offset:0
	v_mul_f32_e32 v171, v82, v82
	v_fmac_f32_e32 v171, v83, v83
	v_fmac_f32_e32 v171, v84, v84
	v_fmac_f32_e32 v171, v85, v85
	s_waitcnt vmcnt(7)
	v_pk_fma_f32 v[86:87], v[86:87], v[134:135], v[150:151]
	v_pk_fma_f32 v[88:89], v[88:89], v[136:137], v[152:153]
	global_store_dwordx4 v[176:177], v[86:89], off offset:32
	v_fmac_f32_e32 v171, v86, v86
	v_fmac_f32_e32 v171, v87, v87
	v_fmac_f32_e32 v171, v88, v88
	v_fmac_f32_e32 v171, v89, v89
	s_waitcnt vmcnt(7)
	v_pk_fma_f32 v[50:51], v[50:51], v[130:131], v[154:155]
	v_pk_fma_f32 v[52:53], v[52:53], v[132:133], v[156:157]
	global_store_dwordx4 v[178:179], v[50:53], off offset:0
	v_mul_f32_e32 v172, v50, v50
	v_fmac_f32_e32 v172, v51, v51
	v_fmac_f32_e32 v172, v52, v52
	v_fmac_f32_e32 v172, v53, v53
	s_waitcnt vmcnt(7)
	v_pk_fma_f32 v[54:55], v[54:55], v[134:135], v[158:159]
	v_pk_fma_f32 v[56:57], v[56:57], v[136:137], v[160:161]
	global_store_dwordx4 v[178:179], v[54:57], off offset:32
	v_fmac_f32_e32 v172, v54, v54
	v_fmac_f32_e32 v172, v55, v55
	v_fmac_f32_e32 v172, v56, v56
	v_fmac_f32_e32 v172, v57, v57
	s_waitcnt vmcnt(7)
	v_pk_fma_f32 v[18:19], v[18:19], v[130:131], v[162:163]
	v_pk_fma_f32 v[20:21], v[20:21], v[132:133], v[164:165]
	global_store_dwordx4 v[180:181], v[18:21], off offset:0
	v_mul_f32_e32 v173, v18, v18
	v_fmac_f32_e32 v173, v19, v19
	v_fmac_f32_e32 v173, v20, v20
	v_fmac_f32_e32 v173, v21, v21
	s_waitcnt vmcnt(7)
	v_pk_fma_f32 v[22:23], v[22:23], v[134:135], v[166:167]
	v_pk_fma_f32 v[24:25], v[24:25], v[136:137], v[168:169]
	global_store_dwordx4 v[180:181], v[22:25], off offset:32
	v_fmac_f32_e32 v173, v22, v22
	v_fmac_f32_e32 v173, v23, v23
	v_fmac_f32_e32 v173, v24, v24
	v_fmac_f32_e32 v173, v25, v25
	global_load_dwordx4 v[130:133], v[182:183], off offset:64
	global_load_dwordx4 v[134:137], v[182:183], off offset:96
	global_load_dwordx4 v[138:141], v[174:175], off offset:64
	global_load_dwordx4 v[142:145], v[174:175], off offset:96
	global_load_dwordx4 v[146:149], v[176:177], off offset:64
	global_load_dwordx4 v[150:153], v[176:177], off offset:96
	global_load_dwordx4 v[154:157], v[178:179], off offset:64
	global_load_dwordx4 v[158:161], v[178:179], off offset:96
	global_load_dwordx4 v[162:165], v[180:181], off offset:64
	global_load_dwordx4 v[166:169], v[180:181], off offset:96
	s_waitcnt vmcnt(7)
	v_pk_fma_f32 v[122:123], v[122:123], v[130:131], v[138:139]
	v_pk_fma_f32 v[124:125], v[124:125], v[132:133], v[140:141]
	global_store_dwordx4 v[174:175], v[122:125], off offset:64
	v_fmac_f32_e32 v170, v122, v122
	v_fmac_f32_e32 v170, v123, v123
	v_fmac_f32_e32 v170, v124, v124
	v_fmac_f32_e32 v170, v125, v125
	s_waitcnt vmcnt(7)
	v_pk_fma_f32 v[126:127], v[126:127], v[134:135], v[142:143]
	v_pk_fma_f32 v[128:129], v[128:129], v[136:137], v[144:145]
	global_store_dwordx4 v[174:175], v[126:129], off offset:96
	v_fmac_f32_e32 v170, v126, v126
	v_fmac_f32_e32 v170, v127, v127
	v_fmac_f32_e32 v170, v128, v128
	v_fmac_f32_e32 v170, v129, v129
	s_waitcnt vmcnt(7)
	v_pk_fma_f32 v[90:91], v[90:91], v[130:131], v[146:147]
	v_pk_fma_f32 v[92:93], v[92:93], v[132:133], v[148:149]
	global_store_dwordx4 v[176:177], v[90:93], off offset:64
	v_fmac_f32_e32 v171, v90, v90
	v_fmac_f32_e32 v171, v91, v91
	v_fmac_f32_e32 v171, v92, v92
	v_fmac_f32_e32 v171, v93, v93
	s_waitcnt vmcnt(7)
	v_pk_fma_f32 v[94:95], v[94:95], v[134:135], v[150:151]
	v_pk_fma_f32 v[96:97], v[96:97], v[136:137], v[152:153]
	global_store_dwordx4 v[176:177], v[94:97], off offset:96
	v_fmac_f32_e32 v171, v94, v94
	v_fmac_f32_e32 v171, v95, v95
	v_fmac_f32_e32 v171, v96, v96
	v_fmac_f32_e32 v171, v97, v97
	s_waitcnt vmcnt(7)
	v_pk_fma_f32 v[58:59], v[58:59], v[130:131], v[154:155]
	v_pk_fma_f32 v[60:61], v[60:61], v[132:133], v[156:157]
	global_store_dwordx4 v[178:179], v[58:61], off offset:64
	v_fmac_f32_e32 v172, v58, v58
	v_fmac_f32_e32 v172, v59, v59
	v_fmac_f32_e32 v172, v60, v60
	v_fmac_f32_e32 v172, v61, v61
	s_waitcnt vmcnt(7)
	v_pk_fma_f32 v[62:63], v[62:63], v[134:135], v[158:159]
	v_pk_fma_f32 v[64:65], v[64:65], v[136:137], v[160:161]
	global_store_dwordx4 v[178:179], v[62:65], off offset:96
	v_fmac_f32_e32 v172, v62, v62
	v_fmac_f32_e32 v172, v63, v63
	v_fmac_f32_e32 v172, v64, v64
	v_fmac_f32_e32 v172, v65, v65
	s_waitcnt vmcnt(7)
	v_pk_fma_f32 v[26:27], v[26:27], v[130:131], v[162:163]
	v_pk_fma_f32 v[28:29], v[28:29], v[132:133], v[164:165]
	global_store_dwordx4 v[180:181], v[26:29], off offset:64
	v_fmac_f32_e32 v173, v26, v26
	v_fmac_f32_e32 v173, v27, v27
	v_fmac_f32_e32 v173, v28, v28
	v_fmac_f32_e32 v173, v29, v29
	s_waitcnt vmcnt(7)
	v_pk_fma_f32 v[30:31], v[30:31], v[134:135], v[166:167]
	v_pk_fma_f32 v[32:33], v[32:33], v[136:137], v[168:169]
	global_store_dwordx4 v[180:181], v[30:33], off offset:96
	v_fmac_f32_e32 v173, v30, v30
	v_fmac_f32_e32 v173, v31, v31
	v_fmac_f32_e32 v173, v32, v32
	v_fmac_f32_e32 v173, v33, v33
	global_load_dwordx4 v[130:133], v[182:183], off offset:128
	global_load_dwordx4 v[134:137], v[182:183], off offset:160
	global_load_dwordx4 v[138:141], v[174:175], off offset:128
	global_load_dwordx4 v[142:145], v[174:175], off offset:160
	global_load_dwordx4 v[146:149], v[176:177], off offset:128
	global_load_dwordx4 v[150:153], v[176:177], off offset:160
	global_load_dwordx4 v[154:157], v[178:179], off offset:128
	global_load_dwordx4 v[158:161], v[178:179], off offset:160
	global_load_dwordx4 v[162:165], v[180:181], off offset:128
	global_load_dwordx4 v[166:169], v[180:181], off offset:160
	s_waitcnt vmcnt(7)
	v_pk_fma_f32 v[98:99], v[98:99], v[130:131], v[138:139]
	v_pk_fma_f32 v[100:101], v[100:101], v[132:133], v[140:141]
	global_store_dwordx4 v[174:175], v[98:101], off offset:128
	v_fmac_f32_e32 v170, v98, v98
	v_fmac_f32_e32 v170, v99, v99
	v_fmac_f32_e32 v170, v100, v100
	v_fmac_f32_e32 v170, v101, v101
	s_waitcnt vmcnt(7)
	v_pk_fma_f32 v[102:103], v[102:103], v[134:135], v[142:143]
	v_pk_fma_f32 v[104:105], v[104:105], v[136:137], v[144:145]
	global_store_dwordx4 v[174:175], v[102:105], off offset:160
	v_fmac_f32_e32 v170, v102, v102
	v_fmac_f32_e32 v170, v103, v103
	v_fmac_f32_e32 v170, v104, v104
	v_fmac_f32_e32 v170, v105, v105
	s_waitcnt vmcnt(7)
	v_pk_fma_f32 v[66:67], v[66:67], v[130:131], v[146:147]
	v_pk_fma_f32 v[68:69], v[68:69], v[132:133], v[148:149]
	global_store_dwordx4 v[176:177], v[66:69], off offset:128
	v_fmac_f32_e32 v171, v66, v66
	v_fmac_f32_e32 v171, v67, v67
	v_fmac_f32_e32 v171, v68, v68
	v_fmac_f32_e32 v171, v69, v69
	s_waitcnt vmcnt(7)
	v_pk_fma_f32 v[70:71], v[70:71], v[134:135], v[150:151]
	v_pk_fma_f32 v[72:73], v[72:73], v[136:137], v[152:153]
	global_store_dwordx4 v[176:177], v[70:73], off offset:160
	v_fmac_f32_e32 v171, v70, v70
	v_fmac_f32_e32 v171, v71, v71
	v_fmac_f32_e32 v171, v72, v72
	v_fmac_f32_e32 v171, v73, v73
	s_waitcnt vmcnt(7)
	v_pk_fma_f32 v[34:35], v[34:35], v[130:131], v[154:155]
	v_pk_fma_f32 v[36:37], v[36:37], v[132:133], v[156:157]
	global_store_dwordx4 v[178:179], v[34:37], off offset:128
	v_fmac_f32_e32 v172, v34, v34
	v_fmac_f32_e32 v172, v35, v35
	v_fmac_f32_e32 v172, v36, v36
	v_fmac_f32_e32 v172, v37, v37
	s_waitcnt vmcnt(7)
	v_pk_fma_f32 v[38:39], v[38:39], v[134:135], v[158:159]
	v_pk_fma_f32 v[40:41], v[40:41], v[136:137], v[160:161]
	global_store_dwordx4 v[178:179], v[38:41], off offset:160
	v_fmac_f32_e32 v172, v38, v38
	v_fmac_f32_e32 v172, v39, v39
	v_fmac_f32_e32 v172, v40, v40
	v_fmac_f32_e32 v172, v41, v41
	s_waitcnt vmcnt(7)
	v_pk_fma_f32 v[2:3], v[2:3], v[130:131], v[162:163]
	v_pk_fma_f32 v[4:5], v[4:5], v[132:133], v[164:165]
	global_store_dwordx4 v[180:181], v[2:5], off offset:128
	v_fmac_f32_e32 v173, v2, v2
	v_fmac_f32_e32 v173, v3, v3
	v_fmac_f32_e32 v173, v4, v4
	v_fmac_f32_e32 v173, v5, v5
	s_waitcnt vmcnt(7)
	v_pk_fma_f32 v[6:7], v[6:7], v[134:135], v[166:167]
	v_pk_fma_f32 v[8:9], v[8:9], v[136:137], v[168:169]
	global_store_dwordx4 v[180:181], v[6:9], off offset:160
	v_fmac_f32_e32 v173, v6, v6
	v_fmac_f32_e32 v173, v7, v7
	v_fmac_f32_e32 v173, v8, v8
	v_fmac_f32_e32 v173, v9, v9
	global_load_dwordx4 v[130:133], v[182:183], off offset:192
	global_load_dwordx4 v[134:137], v[182:183], off offset:224
	global_load_dwordx4 v[138:141], v[174:175], off offset:192
	global_load_dwordx4 v[142:145], v[174:175], off offset:224
	global_load_dwordx4 v[146:149], v[176:177], off offset:192
	global_load_dwordx4 v[150:153], v[176:177], off offset:224
	global_load_dwordx4 v[154:157], v[178:179], off offset:192
	global_load_dwordx4 v[158:161], v[178:179], off offset:224
	global_load_dwordx4 v[162:165], v[180:181], off offset:192
	global_load_dwordx4 v[166:169], v[180:181], off offset:224
	s_waitcnt vmcnt(7)
	v_pk_fma_f32 v[106:107], v[106:107], v[130:131], v[138:139]
	v_pk_fma_f32 v[108:109], v[108:109], v[132:133], v[140:141]
	global_store_dwordx4 v[174:175], v[106:109], off offset:192
	v_fmac_f32_e32 v170, v106, v106
	v_fmac_f32_e32 v170, v107, v107
	v_fmac_f32_e32 v170, v108, v108
	v_fmac_f32_e32 v170, v109, v109
	s_waitcnt vmcnt(7)
	v_pk_fma_f32 v[110:111], v[110:111], v[134:135], v[142:143]
	v_pk_fma_f32 v[112:113], v[112:113], v[136:137], v[144:145]
	global_store_dwordx4 v[174:175], v[110:113], off offset:224
	v_fmac_f32_e32 v170, v110, v110
	v_fmac_f32_e32 v170, v111, v111
	v_fmac_f32_e32 v170, v112, v112
	v_fmac_f32_e32 v170, v113, v113
	s_waitcnt vmcnt(7)
	v_pk_fma_f32 v[74:75], v[74:75], v[130:131], v[146:147]
	v_pk_fma_f32 v[76:77], v[76:77], v[132:133], v[148:149]
	global_store_dwordx4 v[176:177], v[74:77], off offset:192
	v_fmac_f32_e32 v171, v74, v74
	v_fmac_f32_e32 v171, v75, v75
	v_fmac_f32_e32 v171, v76, v76
	v_fmac_f32_e32 v171, v77, v77
	s_waitcnt vmcnt(7)
	v_pk_fma_f32 v[78:79], v[78:79], v[134:135], v[150:151]
	v_pk_fma_f32 v[80:81], v[80:81], v[136:137], v[152:153]
	global_store_dwordx4 v[176:177], v[78:81], off offset:224
	v_fmac_f32_e32 v171, v78, v78
	v_fmac_f32_e32 v171, v79, v79
	v_fmac_f32_e32 v171, v80, v80
	v_fmac_f32_e32 v171, v81, v81
	s_waitcnt vmcnt(7)
	v_pk_fma_f32 v[42:43], v[42:43], v[130:131], v[154:155]
	v_pk_fma_f32 v[44:45], v[44:45], v[132:133], v[156:157]
	global_store_dwordx4 v[178:179], v[42:45], off offset:192
	v_fmac_f32_e32 v172, v42, v42
	v_fmac_f32_e32 v172, v43, v43
	v_fmac_f32_e32 v172, v44, v44
	v_fmac_f32_e32 v172, v45, v45
	s_waitcnt vmcnt(7)
	v_pk_fma_f32 v[46:47], v[46:47], v[134:135], v[158:159]
	v_pk_fma_f32 v[48:49], v[48:49], v[136:137], v[160:161]
	global_store_dwordx4 v[178:179], v[46:49], off offset:224
	v_fmac_f32_e32 v172, v46, v46
	v_fmac_f32_e32 v172, v47, v47
	v_fmac_f32_e32 v172, v48, v48
	v_fmac_f32_e32 v172, v49, v49
	s_waitcnt vmcnt(7)
	v_pk_fma_f32 v[10:11], v[10:11], v[130:131], v[162:163]
	v_pk_fma_f32 v[12:13], v[12:13], v[132:133], v[164:165]
	global_store_dwordx4 v[180:181], v[10:13], off offset:192
	v_fmac_f32_e32 v173, v10, v10
	v_fmac_f32_e32 v173, v11, v11
	v_fmac_f32_e32 v173, v12, v12
	v_fmac_f32_e32 v173, v13, v13
	s_waitcnt vmcnt(7)
	v_pk_fma_f32 v[14:15], v[14:15], v[134:135], v[166:167]
	v_pk_fma_f32 v[16:17], v[16:17], v[136:137], v[168:169]
	global_store_dwordx4 v[180:181], v[14:17], off offset:224
	v_fmac_f32_e32 v173, v14, v14
	v_fmac_f32_e32 v173, v15, v15
	v_fmac_f32_e32 v173, v16, v16
	v_fmac_f32_e32 v173, v17, v17
	v_and_b32_e32 v190, 63, v189
	v_xor_b32_e32 v190, 32, v190
	v_lshlrev_b32_e32 v190, 2, v190
	ds_bpermute_b32 v130, v190, v170
	ds_bpermute_b32 v131, v190, v171
	ds_bpermute_b32 v132, v190, v172
	ds_bpermute_b32 v133, v190, v173
	s_waitcnt lgkmcnt(0)
	v_add_f32_e32 v170, v170, v130
	v_add_f32_e32 v171, v171, v131
	v_add_f32_e32 v172, v172, v132
	v_add_f32_e32 v173, v173, v133
	v_and_b32_e32 v190, 32, v189
	v_cmp_eq_u32_e32 vcc, 0, v190
	s_and_saveexec_b64 s[12:13], vcc
	global_atomic_add_f32 v170, v[184:185], v170, off offset:0 sc0
	global_atomic_add_f32 v171, v[184:185], v171, off offset:128 sc0
	global_atomic_add_f32 v172, v[184:185], v172, off offset:256 sc0
	global_atomic_add_f32 v173, v[184:185], v173, off offset:384 sc0
	s_mov_b64 exec, s[12:13]
	s_waitcnt vmcnt(0)
	s_barrier
	v_cmp_eq_u32_e32 vcc, 0, v189
	s_and_saveexec_b64 s[12:13], vcc
	s_cbranch_execz .Lrs_ffn_skip_n
	s_load_dwordx2 s[10:11], s[0:1], 0xe0
	s_lshl_b32 s100, s20, 1
	s_add_u32 s100, s100, 1
	s_lshl_b32 s100, s100, 6
	s_add_u32 s100, s100, s70
	s_add_u32 s100, s100, 3520
	s_lshl_b32 s100, s100, 2
	s_add_u32 s100, s100, 0x15640000
	s_waitcnt lgkmcnt(0)
	s_add_u32 s10, s10, s100
	s_addc_u32 s11, s11, 0
	v_mov_b32_e32 v190, 0
	v_mov_b32_e32 v130, 1
	s_nop 4
	global_atomic_add v190, v130, s[10:11]
	s_mov_b32 s100, 0x400000
.Lrs_ffn_spin_n:
	global_load_dword v131, v190, s[10:11] sc1
	s_waitcnt vmcnt(0)
	v_cmp_gt_u32_e32 vcc, 4, v131
	s_cbranch_vccz .Lrs_ffn_skip_n
	s_sleep 1
	s_sub_u32 s100, s100, 1
	s_cmp_lg_u32 s100, 0
	s_cbranch_scc1 .Lrs_ffn_spin_n
.Lrs_ffn_skip_n:
	s_or_b64 exec, exec, s[12:13]
	s_barrier
	global_load_dword v170, v[184:185], off offset:0 sc1
	global_load_dword v171, v[184:185], off offset:128 sc1
	global_load_dword v172, v[184:185], off offset:256 sc1
	global_load_dword v173, v[184:185], off offset:384 sc1
	s_load_dwordx2 s[10:11], s[0:1], 0x48
	s_add_u32 s100, s20, 1
	s_lshl_b32 s100, s100, 12
	v_and_b32_e32 v190, 0xfff, v192
	v_add_u32_e32 v190, s100, v190
	s_waitcnt lgkmcnt(0)
	v_lshl_add_u64 v[182:183], v[190:191], 0, s[10:11]
	s_load_dwordx2 s[10:11], s[0:1], 0xe0
	s_add_u32 s100, s20, 1
	s_mul_i32 s100, s100, 5
	s_add_u32 s100, s100, s77
	s_mul_i32 s100, s100, 0x6000
	v_and_b32_e32 v190, 0xfff, v192
	v_add_u32_e32 v190, s100, v190
	s_waitcnt lgkmcnt(0)
	v_lshl_add_u64 v[184:185], v[190:191], 0, s[10:11]
	v_add_u32_e32 v190, 0x1000, v190
	v_lshl_add_u64 v[166:167], v[190:191], 0, s[10:11]
	v_lshrrev_b32_e32 v190, 1, v192
	v_add_u32_e32 v190, 0x6640000, v190
	s_mov_b32 s100, 0x10000
	v_lshl_add_u64 v[174:175], v[190:191], 0, s[10:11]
	v_add_u32_e32 v190, s100, v190
	v_lshl_add_u64 v[176:177], v[190:191], 0, s[10:11]
	v_add_u32_e32 v190, s100, v190
	v_lshl_add_u64 v[178:179], v[190:191], 0, s[10:11]
	v_add_u32_e32 v190, s100, v190
	v_lshl_add_u64 v[180:181], v[190:191], 0, s[10:11]
	s_waitcnt vmcnt(0)
	v_mov_b32_e32 v190, 0x358637bd
	v_fmamk_f32 v170, v170, 0x3a800000, v190
	v_fmamk_f32 v171, v171, 0x3a800000, v190
	v_fmamk_f32 v172, v172, 0x3a800000, v190
	v_fmamk_f32 v173, v173, 0x3a800000, v190
	v_rsq_f32_e32 v170, v170
	v_rsq_f32_e32 v171, v171
	v_rsq_f32_e32 v172, v172
	v_rsq_f32_e32 v173, v173
	s_nop 0
	global_load_dwordx4 v[130:133], v[182:183], off offset:0
	global_load_dwordx4 v[134:137], v[182:183], off offset:32
	global_load_dwordx4 v[138:141], v[166:167], off offset:0
	global_load_dwordx4 v[142:145], v[166:167], off offset:32
	global_load_dwordx4 v[146:149], v[184:185], off offset:0
	global_load_dwordx4 v[150:153], v[184:185], off offset:32
	s_waitcnt vmcnt(0)
	v_pk_add_f32 v[138:139], v[138:139], 1.0 op_sel_hi:[1,0]
	v_pk_add_f32 v[140:141], v[140:141], 1.0 op_sel_hi:[1,0]
	v_pk_add_f32 v[142:143], v[142:143], 1.0 op_sel_hi:[1,0]
	v_pk_add_f32 v[144:145], v[144:145], 1.0 op_sel_hi:[1,0]
	v_mul_f32_e32 v154, v114, v170
	v_mul_f32_e32 v155, v115, v170
	v_mul_f32_e32 v156, v116, v170
	v_mul_f32_e32 v157, v117, v170
	v_pk_mul_f32 v[154:155], v[130:131], v[154:155]
	v_pk_mul_f32 v[156:157], v[132:133], v[156:157]
	v_pk_fma_f32 v[154:155], v[154:155], v[138:139], v[146:147]
	v_pk_fma_f32 v[156:157], v[156:157], v[140:141], v[148:149]
	v_cvt_pk_bf16_f32 v162, v154, v155
	v_cvt_pk_bf16_f32 v163, v156, v157
	global_store_dwordx2 v[174:175], v[162:163], off offset:0
	v_mul_f32_e32 v158, v118, v170
	v_mul_f32_e32 v159, v119, v170
	v_mul_f32_e32 v160, v120, v170
	v_mul_f32_e32 v161, v121, v170
	v_pk_mul_f32 v[158:159], v[134:135], v[158:159]
	v_pk_mul_f32 v[160:161], v[136:137], v[160:161]
	v_pk_fma_f32 v[158:159], v[158:159], v[142:143], v[150:151]
	v_pk_fma_f32 v[160:161], v[160:161], v[144:145], v[152:153]
	v_cvt_pk_bf16_f32 v164, v158, v159
	v_cvt_pk_bf16_f32 v165, v160, v161
	global_store_dwordx2 v[174:175], v[164:165], off offset:16
	v_mul_f32_e32 v154, v82, v171
	v_mul_f32_e32 v155, v83, v171
	v_mul_f32_e32 v156, v84, v171
	v_mul_f32_e32 v157, v85, v171
	v_pk_mul_f32 v[154:155], v[130:131], v[154:155]
	v_pk_mul_f32 v[156:157], v[132:133], v[156:157]
	v_pk_fma_f32 v[154:155], v[154:155], v[138:139], v[146:147]
	v_pk_fma_f32 v[156:157], v[156:157], v[140:141], v[148:149]
	v_cvt_pk_bf16_f32 v162, v154, v155
	v_cvt_pk_bf16_f32 v163, v156, v157
	global_store_dwordx2 v[176:177], v[162:163], off offset:0
	v_mul_f32_e32 v158, v86, v171
	v_mul_f32_e32 v159, v87, v171
	v_mul_f32_e32 v160, v88, v171
	v_mul_f32_e32 v161, v89, v171
	v_pk_mul_f32 v[158:159], v[134:135], v[158:159]
	v_pk_mul_f32 v[160:161], v[136:137], v[160:161]
	v_pk_fma_f32 v[158:159], v[158:159], v[142:143], v[150:151]
	v_pk_fma_f32 v[160:161], v[160:161], v[144:145], v[152:153]
	v_cvt_pk_bf16_f32 v164, v158, v159
	v_cvt_pk_bf16_f32 v165, v160, v161
	global_store_dwordx2 v[176:177], v[164:165], off offset:16
	v_mul_f32_e32 v154, v50, v172
	v_mul_f32_e32 v155, v51, v172
	v_mul_f32_e32 v156, v52, v172
	v_mul_f32_e32 v157, v53, v172
	v_pk_mul_f32 v[154:155], v[130:131], v[154:155]
	v_pk_mul_f32 v[156:157], v[132:133], v[156:157]
	v_pk_fma_f32 v[154:155], v[154:155], v[138:139], v[146:147]
	v_pk_fma_f32 v[156:157], v[156:157], v[140:141], v[148:149]
	v_cvt_pk_bf16_f32 v162, v154, v155
	v_cvt_pk_bf16_f32 v163, v156, v157
	global_store_dwordx2 v[178:179], v[162:163], off offset:0
	v_mul_f32_e32 v158, v54, v172
	v_mul_f32_e32 v159, v55, v172
	v_mul_f32_e32 v160, v56, v172
	v_mul_f32_e32 v161, v57, v172
	v_pk_mul_f32 v[158:159], v[134:135], v[158:159]
	v_pk_mul_f32 v[160:161], v[136:137], v[160:161]
	v_pk_fma_f32 v[158:159], v[158:159], v[142:143], v[150:151]
	v_pk_fma_f32 v[160:161], v[160:161], v[144:145], v[152:153]
	v_cvt_pk_bf16_f32 v164, v158, v159
	v_cvt_pk_bf16_f32 v165, v160, v161
	global_store_dwordx2 v[178:179], v[164:165], off offset:16
	v_mul_f32_e32 v154, v18, v173
	v_mul_f32_e32 v155, v19, v173
	v_mul_f32_e32 v156, v20, v173
	v_mul_f32_e32 v157, v21, v173
	v_pk_mul_f32 v[154:155], v[130:131], v[154:155]
	v_pk_mul_f32 v[156:157], v[132:133], v[156:157]
	v_pk_fma_f32 v[154:155], v[154:155], v[138:139], v[146:147]
	v_pk_fma_f32 v[156:157], v[156:157], v[140:141], v[148:149]
	v_cvt_pk_bf16_f32 v162, v154, v155
	v_cvt_pk_bf16_f32 v163, v156, v157
	global_store_dwordx2 v[180:181], v[162:163], off offset:0
	v_mul_f32_e32 v158, v22, v173
	v_mul_f32_e32 v159, v23, v173
	v_mul_f32_e32 v160, v24, v173
	v_mul_f32_e32 v161, v25, v173
	v_pk_mul_f32 v[158:159], v[134:135], v[158:159]
	v_pk_mul_f32 v[160:161], v[136:137], v[160:161]
	v_pk_fma_f32 v[158:159], v[158:159], v[142:143], v[150:151]
	v_pk_fma_f32 v[160:161], v[160:161], v[144:145], v[152:153]
	v_cvt_pk_bf16_f32 v164, v158, v159
	v_cvt_pk_bf16_f32 v165, v160, v161
	global_store_dwordx2 v[180:181], v[164:165], off offset:16
	global_load_dwordx4 v[130:133], v[182:183], off offset:64
	global_load_dwordx4 v[134:137], v[182:183], off offset:96
	global_load_dwordx4 v[138:141], v[166:167], off offset:64
	global_load_dwordx4 v[142:145], v[166:167], off offset:96
	global_load_dwordx4 v[146:149], v[184:185], off offset:64
	global_load_dwordx4 v[150:153], v[184:185], off offset:96
	s_waitcnt vmcnt(0)
	v_pk_add_f32 v[138:139], v[138:139], 1.0 op_sel_hi:[1,0]
	v_pk_add_f32 v[140:141], v[140:141], 1.0 op_sel_hi:[1,0]
	v_pk_add_f32 v[142:143], v[142:143], 1.0 op_sel_hi:[1,0]
	v_pk_add_f32 v[144:145], v[144:145], 1.0 op_sel_hi:[1,0]
	v_mul_f32_e32 v154, v122, v170
	v_mul_f32_e32 v155, v123, v170
	v_mul_f32_e32 v156, v124, v170
	v_mul_f32_e32 v157, v125, v170
	v_pk_mul_f32 v[154:155], v[130:131], v[154:155]
	v_pk_mul_f32 v[156:157], v[132:133], v[156:157]
	v_pk_fma_f32 v[154:155], v[154:155], v[138:139], v[146:147]
	v_pk_fma_f32 v[156:157], v[156:157], v[140:141], v[148:149]
	v_cvt_pk_bf16_f32 v162, v154, v155
	v_cvt_pk_bf16_f32 v163, v156, v157
	global_store_dwordx2 v[174:175], v[162:163], off offset:32
	v_mul_f32_e32 v158, v126, v170
	v_mul_f32_e32 v159, v127, v170
	v_mul_f32_e32 v160, v128, v170
	v_mul_f32_e32 v161, v129, v170
	v_pk_mul_f32 v[158:159], v[134:135], v[158:159]
	v_pk_mul_f32 v[160:161], v[136:137], v[160:161]
	v_pk_fma_f32 v[158:159], v[158:159], v[142:143], v[150:151]
	v_pk_fma_f32 v[160:161], v[160:161], v[144:145], v[152:153]
	v_cvt_pk_bf16_f32 v164, v158, v159
	v_cvt_pk_bf16_f32 v165, v160, v161
	global_store_dwordx2 v[174:175], v[164:165], off offset:48
	v_mul_f32_e32 v154, v90, v171
	v_mul_f32_e32 v155, v91, v171
	v_mul_f32_e32 v156, v92, v171
	v_mul_f32_e32 v157, v93, v171
	v_pk_mul_f32 v[154:155], v[130:131], v[154:155]
	v_pk_mul_f32 v[156:157], v[132:133], v[156:157]
	v_pk_fma_f32 v[154:155], v[154:155], v[138:139], v[146:147]
	v_pk_fma_f32 v[156:157], v[156:157], v[140:141], v[148:149]
	v_cvt_pk_bf16_f32 v162, v154, v155
	v_cvt_pk_bf16_f32 v163, v156, v157
	global_store_dwordx2 v[176:177], v[162:163], off offset:32
	v_mul_f32_e32 v158, v94, v171
	v_mul_f32_e32 v159, v95, v171
	v_mul_f32_e32 v160, v96, v171
	v_mul_f32_e32 v161, v97, v171
	v_pk_mul_f32 v[158:159], v[134:135], v[158:159]
	v_pk_mul_f32 v[160:161], v[136:137], v[160:161]
	v_pk_fma_f32 v[158:159], v[158:159], v[142:143], v[150:151]
	v_pk_fma_f32 v[160:161], v[160:161], v[144:145], v[152:153]
	v_cvt_pk_bf16_f32 v164, v158, v159
	v_cvt_pk_bf16_f32 v165, v160, v161
	global_store_dwordx2 v[176:177], v[164:165], off offset:48
	v_mul_f32_e32 v154, v58, v172
	v_mul_f32_e32 v155, v59, v172
	v_mul_f32_e32 v156, v60, v172
	v_mul_f32_e32 v157, v61, v172
	v_pk_mul_f32 v[154:155], v[130:131], v[154:155]
	v_pk_mul_f32 v[156:157], v[132:133], v[156:157]
	v_pk_fma_f32 v[154:155], v[154:155], v[138:139], v[146:147]
	v_pk_fma_f32 v[156:157], v[156:157], v[140:141], v[148:149]
	v_cvt_pk_bf16_f32 v162, v154, v155
	v_cvt_pk_bf16_f32 v163, v156, v157
	global_store_dwordx2 v[178:179], v[162:163], off offset:32
	v_mul_f32_e32 v158, v62, v172
	v_mul_f32_e32 v159, v63, v172
	v_mul_f32_e32 v160, v64, v172
	v_mul_f32_e32 v161, v65, v172
	v_pk_mul_f32 v[158:159], v[134:135], v[158:159]
	v_pk_mul_f32 v[160:161], v[136:137], v[160:161]
	v_pk_fma_f32 v[158:159], v[158:159], v[142:143], v[150:151]
	v_pk_fma_f32 v[160:161], v[160:161], v[144:145], v[152:153]
	v_cvt_pk_bf16_f32 v164, v158, v159
	v_cvt_pk_bf16_f32 v165, v160, v161
	global_store_dwordx2 v[178:179], v[164:165], off offset:48
	v_mul_f32_e32 v154, v26, v173
	v_mul_f32_e32 v155, v27, v173
	v_mul_f32_e32 v156, v28, v173
	v_mul_f32_e32 v157, v29, v173
	v_pk_mul_f32 v[154:155], v[130:131], v[154:155]
	v_pk_mul_f32 v[156:157], v[132:133], v[156:157]
	v_pk_fma_f32 v[154:155], v[154:155], v[138:139], v[146:147]
	v_pk_fma_f32 v[156:157], v[156:157], v[140:141], v[148:149]
	v_cvt_pk_bf16_f32 v162, v154, v155
	v_cvt_pk_bf16_f32 v163, v156, v157
	global_store_dwordx2 v[180:181], v[162:163], off offset:32
	v_mul_f32_e32 v158, v30, v173
	v_mul_f32_e32 v159, v31, v173
	v_mul_f32_e32 v160, v32, v173
	v_mul_f32_e32 v161, v33, v173
	v_pk_mul_f32 v[158:159], v[134:135], v[158:159]
	v_pk_mul_f32 v[160:161], v[136:137], v[160:161]
	v_pk_fma_f32 v[158:159], v[158:159], v[142:143], v[150:151]
	v_pk_fma_f32 v[160:161], v[160:161], v[144:145], v[152:153]
	v_cvt_pk_bf16_f32 v164, v158, v159
	v_cvt_pk_bf16_f32 v165, v160, v161
	global_store_dwordx2 v[180:181], v[164:165], off offset:48
	global_load_dwordx4 v[130:133], v[182:183], off offset:128
	global_load_dwordx4 v[134:137], v[182:183], off offset:160
	global_load_dwordx4 v[138:141], v[166:167], off offset:128
	global_load_dwordx4 v[142:145], v[166:167], off offset:160
	global_load_dwordx4 v[146:149], v[184:185], off offset:128
	global_load_dwordx4 v[150:153], v[184:185], off offset:160
	s_waitcnt vmcnt(0)
	v_pk_add_f32 v[138:139], v[138:139], 1.0 op_sel_hi:[1,0]
	v_pk_add_f32 v[140:141], v[140:141], 1.0 op_sel_hi:[1,0]
	v_pk_add_f32 v[142:143], v[142:143], 1.0 op_sel_hi:[1,0]
	v_pk_add_f32 v[144:145], v[144:145], 1.0 op_sel_hi:[1,0]
	v_mul_f32_e32 v154, v98, v170
	v_mul_f32_e32 v155, v99, v170
	v_mul_f32_e32 v156, v100, v170
	v_mul_f32_e32 v157, v101, v170
	v_pk_mul_f32 v[154:155], v[130:131], v[154:155]
	v_pk_mul_f32 v[156:157], v[132:133], v[156:157]
	v_pk_fma_f32 v[154:155], v[154:155], v[138:139], v[146:147]
	v_pk_fma_f32 v[156:157], v[156:157], v[140:141], v[148:149]
	v_cvt_pk_bf16_f32 v162, v154, v155
	v_cvt_pk_bf16_f32 v163, v156, v157
	global_store_dwordx2 v[174:175], v[162:163], off offset:64
	v_mul_f32_e32 v158, v102, v170
	v_mul_f32_e32 v159, v103, v170
	v_mul_f32_e32 v160, v104, v170
	v_mul_f32_e32 v161, v105, v170
	v_pk_mul_f32 v[158:159], v[134:135], v[158:159]
	v_pk_mul_f32 v[160:161], v[136:137], v[160:161]
	v_pk_fma_f32 v[158:159], v[158:159], v[142:143], v[150:151]
	v_pk_fma_f32 v[160:161], v[160:161], v[144:145], v[152:153]
	v_cvt_pk_bf16_f32 v164, v158, v159
	v_cvt_pk_bf16_f32 v165, v160, v161
	global_store_dwordx2 v[174:175], v[164:165], off offset:80
	v_mul_f32_e32 v154, v66, v171
	v_mul_f32_e32 v155, v67, v171
	v_mul_f32_e32 v156, v68, v171
	v_mul_f32_e32 v157, v69, v171
	v_pk_mul_f32 v[154:155], v[130:131], v[154:155]
	v_pk_mul_f32 v[156:157], v[132:133], v[156:157]
	v_pk_fma_f32 v[154:155], v[154:155], v[138:139], v[146:147]
	v_pk_fma_f32 v[156:157], v[156:157], v[140:141], v[148:149]
	v_cvt_pk_bf16_f32 v162, v154, v155
	v_cvt_pk_bf16_f32 v163, v156, v157
	global_store_dwordx2 v[176:177], v[162:163], off offset:64
	v_mul_f32_e32 v158, v70, v171
	v_mul_f32_e32 v159, v71, v171
	v_mul_f32_e32 v160, v72, v171
	v_mul_f32_e32 v161, v73, v171
	v_pk_mul_f32 v[158:159], v[134:135], v[158:159]
	v_pk_mul_f32 v[160:161], v[136:137], v[160:161]
	v_pk_fma_f32 v[158:159], v[158:159], v[142:143], v[150:151]
	v_pk_fma_f32 v[160:161], v[160:161], v[144:145], v[152:153]
	v_cvt_pk_bf16_f32 v164, v158, v159
	v_cvt_pk_bf16_f32 v165, v160, v161
	global_store_dwordx2 v[176:177], v[164:165], off offset:80
	v_mul_f32_e32 v154, v34, v172
	v_mul_f32_e32 v155, v35, v172
	v_mul_f32_e32 v156, v36, v172
	v_mul_f32_e32 v157, v37, v172
	v_pk_mul_f32 v[154:155], v[130:131], v[154:155]
	v_pk_mul_f32 v[156:157], v[132:133], v[156:157]
	v_pk_fma_f32 v[154:155], v[154:155], v[138:139], v[146:147]
	v_pk_fma_f32 v[156:157], v[156:157], v[140:141], v[148:149]
	v_cvt_pk_bf16_f32 v162, v154, v155
	v_cvt_pk_bf16_f32 v163, v156, v157
	global_store_dwordx2 v[178:179], v[162:163], off offset:64
	v_mul_f32_e32 v158, v38, v172
	v_mul_f32_e32 v159, v39, v172
	v_mul_f32_e32 v160, v40, v172
	v_mul_f32_e32 v161, v41, v172
	v_pk_mul_f32 v[158:159], v[134:135], v[158:159]
	v_pk_mul_f32 v[160:161], v[136:137], v[160:161]
	v_pk_fma_f32 v[158:159], v[158:159], v[142:143], v[150:151]
	v_pk_fma_f32 v[160:161], v[160:161], v[144:145], v[152:153]
	v_cvt_pk_bf16_f32 v164, v158, v159
	v_cvt_pk_bf16_f32 v165, v160, v161
	global_store_dwordx2 v[178:179], v[164:165], off offset:80
	v_mul_f32_e32 v154, v2, v173
	v_mul_f32_e32 v155, v3, v173
	v_mul_f32_e32 v156, v4, v173
	v_mul_f32_e32 v157, v5, v173
	v_pk_mul_f32 v[154:155], v[130:131], v[154:155]
	v_pk_mul_f32 v[156:157], v[132:133], v[156:157]
	v_pk_fma_f32 v[154:155], v[154:155], v[138:139], v[146:147]
	v_pk_fma_f32 v[156:157], v[156:157], v[140:141], v[148:149]
	v_cvt_pk_bf16_f32 v162, v154, v155
	v_cvt_pk_bf16_f32 v163, v156, v157
	global_store_dwordx2 v[180:181], v[162:163], off offset:64
	v_mul_f32_e32 v158, v6, v173
	v_mul_f32_e32 v159, v7, v173
	v_mul_f32_e32 v160, v8, v173
	v_mul_f32_e32 v161, v9, v173
	v_pk_mul_f32 v[158:159], v[134:135], v[158:159]
	v_pk_mul_f32 v[160:161], v[136:137], v[160:161]
	v_pk_fma_f32 v[158:159], v[158:159], v[142:143], v[150:151]
	v_pk_fma_f32 v[160:161], v[160:161], v[144:145], v[152:153]
	v_cvt_pk_bf16_f32 v164, v158, v159
	v_cvt_pk_bf16_f32 v165, v160, v161
	global_store_dwordx2 v[180:181], v[164:165], off offset:80
	global_load_dwordx4 v[130:133], v[182:183], off offset:192
	global_load_dwordx4 v[134:137], v[182:183], off offset:224
	global_load_dwordx4 v[138:141], v[166:167], off offset:192
	global_load_dwordx4 v[142:145], v[166:167], off offset:224
	global_load_dwordx4 v[146:149], v[184:185], off offset:192
	global_load_dwordx4 v[150:153], v[184:185], off offset:224
	s_waitcnt vmcnt(0)
	v_pk_add_f32 v[138:139], v[138:139], 1.0 op_sel_hi:[1,0]
	v_pk_add_f32 v[140:141], v[140:141], 1.0 op_sel_hi:[1,0]
	v_pk_add_f32 v[142:143], v[142:143], 1.0 op_sel_hi:[1,0]
	v_pk_add_f32 v[144:145], v[144:145], 1.0 op_sel_hi:[1,0]
	v_mul_f32_e32 v154, v106, v170
	v_mul_f32_e32 v155, v107, v170
	v_mul_f32_e32 v156, v108, v170
	v_mul_f32_e32 v157, v109, v170
	v_pk_mul_f32 v[154:155], v[130:131], v[154:155]
	v_pk_mul_f32 v[156:157], v[132:133], v[156:157]
	v_pk_fma_f32 v[154:155], v[154:155], v[138:139], v[146:147]
	v_pk_fma_f32 v[156:157], v[156:157], v[140:141], v[148:149]
	v_cvt_pk_bf16_f32 v162, v154, v155
	v_cvt_pk_bf16_f32 v163, v156, v157
	global_store_dwordx2 v[174:175], v[162:163], off offset:96
	v_mul_f32_e32 v158, v110, v170
	v_mul_f32_e32 v159, v111, v170
	v_mul_f32_e32 v160, v112, v170
	v_mul_f32_e32 v161, v113, v170
	v_pk_mul_f32 v[158:159], v[134:135], v[158:159]
	v_pk_mul_f32 v[160:161], v[136:137], v[160:161]
	v_pk_fma_f32 v[158:159], v[158:159], v[142:143], v[150:151]
	v_pk_fma_f32 v[160:161], v[160:161], v[144:145], v[152:153]
	v_cvt_pk_bf16_f32 v164, v158, v159
	v_cvt_pk_bf16_f32 v165, v160, v161
	global_store_dwordx2 v[174:175], v[164:165], off offset:112
	v_mul_f32_e32 v154, v74, v171
	v_mul_f32_e32 v155, v75, v171
	v_mul_f32_e32 v156, v76, v171
	v_mul_f32_e32 v157, v77, v171
	v_pk_mul_f32 v[154:155], v[130:131], v[154:155]
	v_pk_mul_f32 v[156:157], v[132:133], v[156:157]
	v_pk_fma_f32 v[154:155], v[154:155], v[138:139], v[146:147]
	v_pk_fma_f32 v[156:157], v[156:157], v[140:141], v[148:149]
	v_cvt_pk_bf16_f32 v162, v154, v155
	v_cvt_pk_bf16_f32 v163, v156, v157
	global_store_dwordx2 v[176:177], v[162:163], off offset:96
	v_mul_f32_e32 v158, v78, v171
	v_mul_f32_e32 v159, v79, v171
	v_mul_f32_e32 v160, v80, v171
	v_mul_f32_e32 v161, v81, v171
	v_pk_mul_f32 v[158:159], v[134:135], v[158:159]
	v_pk_mul_f32 v[160:161], v[136:137], v[160:161]
	v_pk_fma_f32 v[158:159], v[158:159], v[142:143], v[150:151]
	v_pk_fma_f32 v[160:161], v[160:161], v[144:145], v[152:153]
	v_cvt_pk_bf16_f32 v164, v158, v159
	v_cvt_pk_bf16_f32 v165, v160, v161
	global_store_dwordx2 v[176:177], v[164:165], off offset:112
	v_mul_f32_e32 v154, v42, v172
	v_mul_f32_e32 v155, v43, v172
	v_mul_f32_e32 v156, v44, v172
	v_mul_f32_e32 v157, v45, v172
	v_pk_mul_f32 v[154:155], v[130:131], v[154:155]
	v_pk_mul_f32 v[156:157], v[132:133], v[156:157]
	v_pk_fma_f32 v[154:155], v[154:155], v[138:139], v[146:147]
	v_pk_fma_f32 v[156:157], v[156:157], v[140:141], v[148:149]
	v_cvt_pk_bf16_f32 v162, v154, v155
	v_cvt_pk_bf16_f32 v163, v156, v157
	global_store_dwordx2 v[178:179], v[162:163], off offset:96
	v_mul_f32_e32 v158, v46, v172
	v_mul_f32_e32 v159, v47, v172
	v_mul_f32_e32 v160, v48, v172
	v_mul_f32_e32 v161, v49, v172
	v_pk_mul_f32 v[158:159], v[134:135], v[158:159]
	v_pk_mul_f32 v[160:161], v[136:137], v[160:161]
	v_pk_fma_f32 v[158:159], v[158:159], v[142:143], v[150:151]
	v_pk_fma_f32 v[160:161], v[160:161], v[144:145], v[152:153]
	v_cvt_pk_bf16_f32 v164, v158, v159
	v_cvt_pk_bf16_f32 v165, v160, v161
	global_store_dwordx2 v[178:179], v[164:165], off offset:112
	v_mul_f32_e32 v154, v10, v173
	v_mul_f32_e32 v155, v11, v173
	v_mul_f32_e32 v156, v12, v173
	v_mul_f32_e32 v157, v13, v173
	v_pk_mul_f32 v[154:155], v[130:131], v[154:155]
	v_pk_mul_f32 v[156:157], v[132:133], v[156:157]
	v_pk_fma_f32 v[154:155], v[154:155], v[138:139], v[146:147]
	v_pk_fma_f32 v[156:157], v[156:157], v[140:141], v[148:149]
	v_cvt_pk_bf16_f32 v162, v154, v155
	v_cvt_pk_bf16_f32 v163, v156, v157
	global_store_dwordx2 v[180:181], v[162:163], off offset:96
	v_mul_f32_e32 v158, v14, v173
	v_mul_f32_e32 v159, v15, v173
	v_mul_f32_e32 v160, v16, v173
	v_mul_f32_e32 v161, v17, v173
	v_pk_mul_f32 v[158:159], v[134:135], v[158:159]
	v_pk_mul_f32 v[160:161], v[136:137], v[160:161]
	v_pk_fma_f32 v[158:159], v[158:159], v[142:143], v[150:151]
	v_pk_fma_f32 v[160:161], v[160:161], v[144:145], v[152:153]
	v_cvt_pk_bf16_f32 v164, v158, v159
	v_cvt_pk_bf16_f32 v165, v160, v161
	global_store_dwordx2 v[180:181], v[164:165], off offset:112
	s_mov_b64 exec, -1
	s_branch .LBB0_1306
.Lrs_ffn_final:
	global_load_dwordx4 v[130:133], v[182:183], off offset:0
	global_load_dwordx4 v[134:137], v[182:183], off offset:32
	global_load_dwordx4 v[138:141], v[174:175], off offset:0
	global_load_dwordx4 v[142:145], v[174:175], off offset:32
	global_load_dwordx4 v[146:149], v[176:177], off offset:0
	global_load_dwordx4 v[150:153], v[176:177], off offset:32
	global_load_dwordx4 v[154:157], v[178:179], off offset:0
	global_load_dwordx4 v[158:161], v[178:179], off offset:32
	global_load_dwordx4 v[162:165], v[180:181], off offset:0
	global_load_dwordx4 v[166:169], v[180:181], off offset:32
	s_waitcnt vmcnt(7)
	v_pk_fma_f32 v[114:115], v[114:115], v[130:131], v[138:139]
	v_pk_fma_f32 v[116:117], v[116:117], v[132:133], v[140:141]
	v_mul_f32_e32 v170, v114, v114
	v_fmac_f32_e32 v170, v115, v115
	v_fmac_f32_e32 v170, v116, v116
	v_fmac_f32_e32 v170, v117, v117
	s_waitcnt vmcnt(6)
	v_pk_fma_f32 v[118:119], v[118:119], v[134:135], v[142:143]
	v_pk_fma_f32 v[120:121], v[120:121], v[136:137], v[144:145]
	v_fmac_f32_e32 v170, v118, v118
	v_fmac_f32_e32 v170, v119, v119
	v_fmac_f32_e32 v170, v120, v120
	v_fmac_f32_e32 v170, v121, v121
	s_waitcnt vmcnt(5)
	v_pk_fma_f32 v[82:83], v[82:83], v[130:131], v[146:147]
	v_pk_fma_f32 v[84:85], v[84:85], v[132:133], v[148:149]
	v_mul_f32_e32 v171, v82, v82
	v_fmac_f32_e32 v171, v83, v83
	v_fmac_f32_e32 v171, v84, v84
	v_fmac_f32_e32 v171, v85, v85
	s_waitcnt vmcnt(4)
	v_pk_fma_f32 v[86:87], v[86:87], v[134:135], v[150:151]
	v_pk_fma_f32 v[88:89], v[88:89], v[136:137], v[152:153]
	v_fmac_f32_e32 v171, v86, v86
	v_fmac_f32_e32 v171, v87, v87
	v_fmac_f32_e32 v171, v88, v88
	v_fmac_f32_e32 v171, v89, v89
	s_waitcnt vmcnt(3)
	v_pk_fma_f32 v[50:51], v[50:51], v[130:131], v[154:155]
	v_pk_fma_f32 v[52:53], v[52:53], v[132:133], v[156:157]
	v_mul_f32_e32 v172, v50, v50
	v_fmac_f32_e32 v172, v51, v51
	v_fmac_f32_e32 v172, v52, v52
	v_fmac_f32_e32 v172, v53, v53
	s_waitcnt vmcnt(2)
	v_pk_fma_f32 v[54:55], v[54:55], v[134:135], v[158:159]
	v_pk_fma_f32 v[56:57], v[56:57], v[136:137], v[160:161]
	v_fmac_f32_e32 v172, v54, v54
	v_fmac_f32_e32 v172, v55, v55
	v_fmac_f32_e32 v172, v56, v56
	v_fmac_f32_e32 v172, v57, v57
	s_waitcnt vmcnt(1)
	v_pk_fma_f32 v[18:19], v[18:19], v[130:131], v[162:163]
	v_pk_fma_f32 v[20:21], v[20:21], v[132:133], v[164:165]
	v_mul_f32_e32 v173, v18, v18
	v_fmac_f32_e32 v173, v19, v19
	v_fmac_f32_e32 v173, v20, v20
	v_fmac_f32_e32 v173, v21, v21
	s_waitcnt vmcnt(0)
	v_pk_fma_f32 v[22:23], v[22:23], v[134:135], v[166:167]
	v_pk_fma_f32 v[24:25], v[24:25], v[136:137], v[168:169]
	v_fmac_f32_e32 v173, v22, v22
	v_fmac_f32_e32 v173, v23, v23
	v_fmac_f32_e32 v173, v24, v24
	v_fmac_f32_e32 v173, v25, v25
	global_load_dwordx4 v[130:133], v[182:183], off offset:64
	global_load_dwordx4 v[134:137], v[182:183], off offset:96
	global_load_dwordx4 v[138:141], v[174:175], off offset:64
	global_load_dwordx4 v[142:145], v[174:175], off offset:96
	global_load_dwordx4 v[146:149], v[176:177], off offset:64
	global_load_dwordx4 v[150:153], v[176:177], off offset:96
	global_load_dwordx4 v[154:157], v[178:179], off offset:64
	global_load_dwordx4 v[158:161], v[178:179], off offset:96
	global_load_dwordx4 v[162:165], v[180:181], off offset:64
	global_load_dwordx4 v[166:169], v[180:181], off offset:96
	s_waitcnt vmcnt(7)
	v_pk_fma_f32 v[122:123], v[122:123], v[130:131], v[138:139]
	v_pk_fma_f32 v[124:125], v[124:125], v[132:133], v[140:141]
	v_fmac_f32_e32 v170, v122, v122
	v_fmac_f32_e32 v170, v123, v123
	v_fmac_f32_e32 v170, v124, v124
	v_fmac_f32_e32 v170, v125, v125
	s_waitcnt vmcnt(6)
	v_pk_fma_f32 v[126:127], v[126:127], v[134:135], v[142:143]
	v_pk_fma_f32 v[128:129], v[128:129], v[136:137], v[144:145]
	v_fmac_f32_e32 v170, v126, v126
	v_fmac_f32_e32 v170, v127, v127
	v_fmac_f32_e32 v170, v128, v128
	v_fmac_f32_e32 v170, v129, v129
	s_waitcnt vmcnt(5)
	v_pk_fma_f32 v[90:91], v[90:91], v[130:131], v[146:147]
	v_pk_fma_f32 v[92:93], v[92:93], v[132:133], v[148:149]
	v_fmac_f32_e32 v171, v90, v90
	v_fmac_f32_e32 v171, v91, v91
	v_fmac_f32_e32 v171, v92, v92
	v_fmac_f32_e32 v171, v93, v93
	s_waitcnt vmcnt(4)
	v_pk_fma_f32 v[94:95], v[94:95], v[134:135], v[150:151]
	v_pk_fma_f32 v[96:97], v[96:97], v[136:137], v[152:153]
	v_fmac_f32_e32 v171, v94, v94
	v_fmac_f32_e32 v171, v95, v95
	v_fmac_f32_e32 v171, v96, v96
	v_fmac_f32_e32 v171, v97, v97
	s_waitcnt vmcnt(3)
	v_pk_fma_f32 v[58:59], v[58:59], v[130:131], v[154:155]
	v_pk_fma_f32 v[60:61], v[60:61], v[132:133], v[156:157]
	v_fmac_f32_e32 v172, v58, v58
	v_fmac_f32_e32 v172, v59, v59
	v_fmac_f32_e32 v172, v60, v60
	v_fmac_f32_e32 v172, v61, v61
	s_waitcnt vmcnt(2)
	v_pk_fma_f32 v[62:63], v[62:63], v[134:135], v[158:159]
	v_pk_fma_f32 v[64:65], v[64:65], v[136:137], v[160:161]
	v_fmac_f32_e32 v172, v62, v62
	v_fmac_f32_e32 v172, v63, v63
	v_fmac_f32_e32 v172, v64, v64
	v_fmac_f32_e32 v172, v65, v65
	s_waitcnt vmcnt(1)
	v_pk_fma_f32 v[26:27], v[26:27], v[130:131], v[162:163]
	v_pk_fma_f32 v[28:29], v[28:29], v[132:133], v[164:165]
	v_fmac_f32_e32 v173, v26, v26
	v_fmac_f32_e32 v173, v27, v27
	v_fmac_f32_e32 v173, v28, v28
	v_fmac_f32_e32 v173, v29, v29
	s_waitcnt vmcnt(0)
	v_pk_fma_f32 v[30:31], v[30:31], v[134:135], v[166:167]
	v_pk_fma_f32 v[32:33], v[32:33], v[136:137], v[168:169]
	v_fmac_f32_e32 v173, v30, v30
	v_fmac_f32_e32 v173, v31, v31
	v_fmac_f32_e32 v173, v32, v32
	v_fmac_f32_e32 v173, v33, v33
	global_load_dwordx4 v[130:133], v[182:183], off offset:128
	global_load_dwordx4 v[134:137], v[182:183], off offset:160
	global_load_dwordx4 v[138:141], v[174:175], off offset:128
	global_load_dwordx4 v[142:145], v[174:175], off offset:160
	global_load_dwordx4 v[146:149], v[176:177], off offset:128
	global_load_dwordx4 v[150:153], v[176:177], off offset:160
	global_load_dwordx4 v[154:157], v[178:179], off offset:128
	global_load_dwordx4 v[158:161], v[178:179], off offset:160
	global_load_dwordx4 v[162:165], v[180:181], off offset:128
	global_load_dwordx4 v[166:169], v[180:181], off offset:160
	s_waitcnt vmcnt(7)
	v_pk_fma_f32 v[98:99], v[98:99], v[130:131], v[138:139]
	v_pk_fma_f32 v[100:101], v[100:101], v[132:133], v[140:141]
	v_fmac_f32_e32 v170, v98, v98
	v_fmac_f32_e32 v170, v99, v99
	v_fmac_f32_e32 v170, v100, v100
	v_fmac_f32_e32 v170, v101, v101
	s_waitcnt vmcnt(6)
	v_pk_fma_f32 v[102:103], v[102:103], v[134:135], v[142:143]
	v_pk_fma_f32 v[104:105], v[104:105], v[136:137], v[144:145]
	v_fmac_f32_e32 v170, v102, v102
	v_fmac_f32_e32 v170, v103, v103
	v_fmac_f32_e32 v170, v104, v104
	v_fmac_f32_e32 v170, v105, v105
	s_waitcnt vmcnt(5)
	v_pk_fma_f32 v[66:67], v[66:67], v[130:131], v[146:147]
	v_pk_fma_f32 v[68:69], v[68:69], v[132:133], v[148:149]
	v_fmac_f32_e32 v171, v66, v66
	v_fmac_f32_e32 v171, v67, v67
	v_fmac_f32_e32 v171, v68, v68
	v_fmac_f32_e32 v171, v69, v69
	s_waitcnt vmcnt(4)
	v_pk_fma_f32 v[70:71], v[70:71], v[134:135], v[150:151]
	v_pk_fma_f32 v[72:73], v[72:73], v[136:137], v[152:153]
	v_fmac_f32_e32 v171, v70, v70
	v_fmac_f32_e32 v171, v71, v71
	v_fmac_f32_e32 v171, v72, v72
	v_fmac_f32_e32 v171, v73, v73
	s_waitcnt vmcnt(3)
	v_pk_fma_f32 v[34:35], v[34:35], v[130:131], v[154:155]
	v_pk_fma_f32 v[36:37], v[36:37], v[132:133], v[156:157]
	v_fmac_f32_e32 v172, v34, v34
	v_fmac_f32_e32 v172, v35, v35
	v_fmac_f32_e32 v172, v36, v36
	v_fmac_f32_e32 v172, v37, v37
	s_waitcnt vmcnt(2)
	v_pk_fma_f32 v[38:39], v[38:39], v[134:135], v[158:159]
	v_pk_fma_f32 v[40:41], v[40:41], v[136:137], v[160:161]
	v_fmac_f32_e32 v172, v38, v38
	v_fmac_f32_e32 v172, v39, v39
	v_fmac_f32_e32 v172, v40, v40
	v_fmac_f32_e32 v172, v41, v41
	s_waitcnt vmcnt(1)
	v_pk_fma_f32 v[2:3], v[2:3], v[130:131], v[162:163]
	v_pk_fma_f32 v[4:5], v[4:5], v[132:133], v[164:165]
	v_fmac_f32_e32 v173, v2, v2
	v_fmac_f32_e32 v173, v3, v3
	v_fmac_f32_e32 v173, v4, v4
	v_fmac_f32_e32 v173, v5, v5
	s_waitcnt vmcnt(0)
	v_pk_fma_f32 v[6:7], v[6:7], v[134:135], v[166:167]
	v_pk_fma_f32 v[8:9], v[8:9], v[136:137], v[168:169]
	v_fmac_f32_e32 v173, v6, v6
	v_fmac_f32_e32 v173, v7, v7
	v_fmac_f32_e32 v173, v8, v8
	v_fmac_f32_e32 v173, v9, v9
	global_load_dwordx4 v[130:133], v[182:183], off offset:192
	global_load_dwordx4 v[134:137], v[182:183], off offset:224
	global_load_dwordx4 v[138:141], v[174:175], off offset:192
	global_load_dwordx4 v[142:145], v[174:175], off offset:224
	global_load_dwordx4 v[146:149], v[176:177], off offset:192
	global_load_dwordx4 v[150:153], v[176:177], off offset:224
	global_load_dwordx4 v[154:157], v[178:179], off offset:192
	global_load_dwordx4 v[158:161], v[178:179], off offset:224
	global_load_dwordx4 v[162:165], v[180:181], off offset:192
	global_load_dwordx4 v[166:169], v[180:181], off offset:224
	s_waitcnt vmcnt(7)
	v_pk_fma_f32 v[106:107], v[106:107], v[130:131], v[138:139]
	v_pk_fma_f32 v[108:109], v[108:109], v[132:133], v[140:141]
	v_fmac_f32_e32 v170, v106, v106
	v_fmac_f32_e32 v170, v107, v107
	v_fmac_f32_e32 v170, v108, v108
	v_fmac_f32_e32 v170, v109, v109
	s_waitcnt vmcnt(6)
	v_pk_fma_f32 v[110:111], v[110:111], v[134:135], v[142:143]
	v_pk_fma_f32 v[112:113], v[112:113], v[136:137], v[144:145]
	v_fmac_f32_e32 v170, v110, v110
	v_fmac_f32_e32 v170, v111, v111
	v_fmac_f32_e32 v170, v112, v112
	v_fmac_f32_e32 v170, v113, v113
	s_waitcnt vmcnt(5)
	v_pk_fma_f32 v[74:75], v[74:75], v[130:131], v[146:147]
	v_pk_fma_f32 v[76:77], v[76:77], v[132:133], v[148:149]
	v_fmac_f32_e32 v171, v74, v74
	v_fmac_f32_e32 v171, v75, v75
	v_fmac_f32_e32 v171, v76, v76
	v_fmac_f32_e32 v171, v77, v77
	s_waitcnt vmcnt(4)
	v_pk_fma_f32 v[78:79], v[78:79], v[134:135], v[150:151]
	v_pk_fma_f32 v[80:81], v[80:81], v[136:137], v[152:153]
	v_fmac_f32_e32 v171, v78, v78
	v_fmac_f32_e32 v171, v79, v79
	v_fmac_f32_e32 v171, v80, v80
	v_fmac_f32_e32 v171, v81, v81
	s_waitcnt vmcnt(3)
	v_pk_fma_f32 v[42:43], v[42:43], v[130:131], v[154:155]
	v_pk_fma_f32 v[44:45], v[44:45], v[132:133], v[156:157]
	v_fmac_f32_e32 v172, v42, v42
	v_fmac_f32_e32 v172, v43, v43
	v_fmac_f32_e32 v172, v44, v44
	v_fmac_f32_e32 v172, v45, v45
	s_waitcnt vmcnt(2)
	v_pk_fma_f32 v[46:47], v[46:47], v[134:135], v[158:159]
	v_pk_fma_f32 v[48:49], v[48:49], v[136:137], v[160:161]
	v_fmac_f32_e32 v172, v46, v46
	v_fmac_f32_e32 v172, v47, v47
	v_fmac_f32_e32 v172, v48, v48
	v_fmac_f32_e32 v172, v49, v49
	s_waitcnt vmcnt(1)
	v_pk_fma_f32 v[10:11], v[10:11], v[130:131], v[162:163]
	v_pk_fma_f32 v[12:13], v[12:13], v[132:133], v[164:165]
	v_fmac_f32_e32 v173, v10, v10
	v_fmac_f32_e32 v173, v11, v11
	v_fmac_f32_e32 v173, v12, v12
	v_fmac_f32_e32 v173, v13, v13
	s_waitcnt vmcnt(0)
	v_pk_fma_f32 v[14:15], v[14:15], v[134:135], v[166:167]
	v_pk_fma_f32 v[16:17], v[16:17], v[136:137], v[168:169]
	v_fmac_f32_e32 v173, v14, v14
	v_fmac_f32_e32 v173, v15, v15
	v_fmac_f32_e32 v173, v16, v16
	v_fmac_f32_e32 v173, v17, v17
	v_and_b32_e32 v190, 63, v189
	v_xor_b32_e32 v190, 32, v190
	v_lshlrev_b32_e32 v190, 2, v190
	ds_bpermute_b32 v130, v190, v170
	ds_bpermute_b32 v131, v190, v171
	ds_bpermute_b32 v132, v190, v172
	ds_bpermute_b32 v133, v190, v173
	s_waitcnt lgkmcnt(0)
	v_add_f32_e32 v170, v170, v130
	v_add_f32_e32 v171, v171, v131
	v_add_f32_e32 v172, v172, v132
	v_add_f32_e32 v173, v173, v133
	v_and_b32_e32 v190, 32, v189
	v_cmp_eq_u32_e32 vcc, 0, v190
	s_and_saveexec_b64 s[12:13], vcc
	global_atomic_add_f32 v170, v[184:185], v170, off offset:0 sc0
	global_atomic_add_f32 v171, v[184:185], v171, off offset:128 sc0
	global_atomic_add_f32 v172, v[184:185], v172, off offset:256 sc0
	global_atomic_add_f32 v173, v[184:185], v173, off offset:384 sc0
	s_mov_b64 exec, s[12:13]
	s_waitcnt vmcnt(0)
	s_barrier
	v_cmp_eq_u32_e32 vcc, 0, v189
	s_and_saveexec_b64 s[12:13], vcc
	s_cbranch_execz .Lrs_ffn_skip_f
	s_load_dwordx2 s[10:11], s[0:1], 0xe0
	s_lshl_b32 s100, s20, 1
	s_add_u32 s100, s100, 1
	s_lshl_b32 s100, s100, 6
	s_add_u32 s100, s100, s70
	s_add_u32 s100, s100, 3520
	s_lshl_b32 s100, s100, 2
	s_add_u32 s100, s100, 0x15640000
	s_waitcnt lgkmcnt(0)
	s_add_u32 s10, s10, s100
	s_addc_u32 s11, s11, 0
	v_mov_b32_e32 v190, 0
	v_mov_b32_e32 v130, 1
	s_nop 4
	global_atomic_add v190, v130, s[10:11]
	s_mov_b32 s100, 0x400000

.Lrs_ffn_skip_f:
	s_or_b64 exec, exec, s[12:13]
	s_barrier
	global_load_dword v170, v[184:185], off offset:0 sc1
	global_load_dword v171, v[184:185], off offset:128 sc1
	global_load_dword v172, v[184:185], off offset:256 sc1
	global_load_dword v173, v[184:185], off offset:384 sc1
	s_load_dwordx2 s[10:11], s[0:1], 0xd0
	v_and_b32_e32 v190, 0xfff, v192
	s_waitcnt lgkmcnt(0)
	v_lshl_add_u64 v[182:183], v[190:191], 0, s[10:11]
	s_waitcnt vmcnt(0)
	v_mov_b32_e32 v190, 0x358637bd
	v_fmamk_f32 v170, v170, 0x3a800000, v190
	v_fmamk_f32 v171, v171, 0x3a800000, v190
	v_fmamk_f32 v172, v172, 0x3a800000, v190
	v_fmamk_f32 v173, v173, 0x3a800000, v190
	v_rsq_f32_e32 v170, v170
	v_rsq_f32_e32 v171, v171
	v_rsq_f32_e32 v172, v172
	v_rsq_f32_e32 v173, v173
	s_nop 0
	global_load_dwordx4 v[130:133], v[182:183], off offset:0
	global_load_dwordx4 v[134:137], v[182:183], off offset:32
	s_waitcnt vmcnt(0)
	v_mul_f32_e32 v154, v114, v170
	v_mul_f32_e32 v155, v115, v170
	v_mul_f32_e32 v156, v116, v170
	v_mul_f32_e32 v157, v117, v170
	v_pk_mul_f32 v[154:155], v[130:131], v[154:155]
	v_pk_mul_f32 v[156:157], v[132:133], v[156:157]
	global_store_dwordx4 v[174:175], v[154:157], off offset:0
	v_mul_f32_e32 v158, v118, v170
	v_mul_f32_e32 v159, v119, v170
	v_mul_f32_e32 v160, v120, v170
	v_mul_f32_e32 v161, v121, v170
	v_pk_mul_f32 v[158:159], v[134:135], v[158:159]
	v_pk_mul_f32 v[160:161], v[136:137], v[160:161]
	global_store_dwordx4 v[174:175], v[158:161], off offset:32
	v_mul_f32_e32 v154, v82, v171
	v_mul_f32_e32 v155, v83, v171
	v_mul_f32_e32 v156, v84, v171
	v_mul_f32_e32 v157, v85, v171
	v_pk_mul_f32 v[154:155], v[130:131], v[154:155]
	v_pk_mul_f32 v[156:157], v[132:133], v[156:157]
	global_store_dwordx4 v[176:177], v[154:157], off offset:0
	v_mul_f32_e32 v158, v86, v171
	v_mul_f32_e32 v159, v87, v171
	v_mul_f32_e32 v160, v88, v171
	v_mul_f32_e32 v161, v89, v171
	v_pk_mul_f32 v[158:159], v[134:135], v[158:159]
	v_pk_mul_f32 v[160:161], v[136:137], v[160:161]
	global_store_dwordx4 v[176:177], v[158:161], off offset:32
	v_mul_f32_e32 v154, v50, v172
	v_mul_f32_e32 v155, v51, v172
	v_mul_f32_e32 v156, v52, v172
	v_mul_f32_e32 v157, v53, v172
	v_pk_mul_f32 v[154:155], v[130:131], v[154:155]
	v_pk_mul_f32 v[156:157], v[132:133], v[156:157]
	global_store_dwordx4 v[178:179], v[154:157], off offset:0
	v_mul_f32_e32 v158, v54, v172
	v_mul_f32_e32 v159, v55, v172
	v_mul_f32_e32 v160, v56, v172
	v_mul_f32_e32 v161, v57, v172
	v_pk_mul_f32 v[158:159], v[134:135], v[158:159]
	v_pk_mul_f32 v[160:161], v[136:137], v[160:161]
	global_store_dwordx4 v[178:179], v[158:161], off offset:32
	v_mul_f32_e32 v154, v18, v173
	v_mul_f32_e32 v155, v19, v173
	v_mul_f32_e32 v156, v20, v173
	v_mul_f32_e32 v157, v21, v173
	v_pk_mul_f32 v[154:155], v[130:131], v[154:155]
	v_pk_mul_f32 v[156:157], v[132:133], v[156:157]
	global_store_dwordx4 v[180:181], v[154:157], off offset:0
	v_mul_f32_e32 v158, v22, v173
	v_mul_f32_e32 v159, v23, v173
	v_mul_f32_e32 v160, v24, v173
	v_mul_f32_e32 v161, v25, v173
	v_pk_mul_f32 v[158:159], v[134:135], v[158:159]
	v_pk_mul_f32 v[160:161], v[136:137], v[160:161]
	global_store_dwordx4 v[180:181], v[158:161], off offset:32
	global_load_dwordx4 v[130:133], v[182:183], off offset:64
	global_load_dwordx4 v[134:137], v[182:183], off offset:96
	s_waitcnt vmcnt(0)
	v_mul_f32_e32 v154, v122, v170
	v_mul_f32_e32 v155, v123, v170
	v_mul_f32_e32 v156, v124, v170
	v_mul_f32_e32 v157, v125, v170
	v_pk_mul_f32 v[154:155], v[130:131], v[154:155]
	v_pk_mul_f32 v[156:157], v[132:133], v[156:157]
	global_store_dwordx4 v[174:175], v[154:157], off offset:64
	v_mul_f32_e32 v158, v126, v170
	v_mul_f32_e32 v159, v127, v170
	v_mul_f32_e32 v160, v128, v170
	v_mul_f32_e32 v161, v129, v170
	v_pk_mul_f32 v[158:159], v[134:135], v[158:159]
	v_pk_mul_f32 v[160:161], v[136:137], v[160:161]
	global_store_dwordx4 v[174:175], v[158:161], off offset:96
	v_mul_f32_e32 v154, v90, v171
	v_mul_f32_e32 v155, v91, v171
	v_mul_f32_e32 v156, v92, v171
	v_mul_f32_e32 v157, v93, v171
	v_pk_mul_f32 v[154:155], v[130:131], v[154:155]
	v_pk_mul_f32 v[156:157], v[132:133], v[156:157]
	global_store_dwordx4 v[176:177], v[154:157], off offset:64
	v_mul_f32_e32 v158, v94, v171
	v_mul_f32_e32 v159, v95, v171
	v_mul_f32_e32 v160, v96, v171
	v_mul_f32_e32 v161, v97, v171
	v_pk_mul_f32 v[158:159], v[134:135], v[158:159]
	v_pk_mul_f32 v[160:161], v[136:137], v[160:161]
	global_store_dwordx4 v[176:177], v[158:161], off offset:96
	v_mul_f32_e32 v154, v58, v172
	v_mul_f32_e32 v155, v59, v172
	v_mul_f32_e32 v156, v60, v172
	v_mul_f32_e32 v157, v61, v172
	v_pk_mul_f32 v[154:155], v[130:131], v[154:155]
	v_pk_mul_f32 v[156:157], v[132:133], v[156:157]
	global_store_dwordx4 v[178:179], v[154:157], off offset:64
	v_mul_f32_e32 v158, v62, v172
	v_mul_f32_e32 v159, v63, v172
	v_mul_f32_e32 v160, v64, v172
	v_mul_f32_e32 v161, v65, v172
	v_pk_mul_f32 v[158:159], v[134:135], v[158:159]
	v_pk_mul_f32 v[160:161], v[136:137], v[160:161]
	global_store_dwordx4 v[178:179], v[158:161], off offset:96
	v_mul_f32_e32 v154, v26, v173
	v_mul_f32_e32 v155, v27, v173
	v_mul_f32_e32 v156, v28, v173
	v_mul_f32_e32 v157, v29, v173
	v_pk_mul_f32 v[154:155], v[130:131], v[154:155]
	v_pk_mul_f32 v[156:157], v[132:133], v[156:157]
	global_store_dwordx4 v[180:181], v[154:157], off offset:64
	v_mul_f32_e32 v158, v30, v173
	v_mul_f32_e32 v159, v31, v173
	v_mul_f32_e32 v160, v32, v173
	v_mul_f32_e32 v161, v33, v173
	v_pk_mul_f32 v[158:159], v[134:135], v[158:159]
	v_pk_mul_f32 v[160:161], v[136:137], v[160:161]
	global_store_dwordx4 v[180:181], v[158:161], off offset:96
	global_load_dwordx4 v[130:133], v[182:183], off offset:128
	global_load_dwordx4 v[134:137], v[182:183], off offset:160
	s_waitcnt vmcnt(0)
	v_mul_f32_e32 v154, v98, v170
	v_mul_f32_e32 v155, v99, v170
	v_mul_f32_e32 v156, v100, v170
	v_mul_f32_e32 v157, v101, v170
	v_pk_mul_f32 v[154:155], v[130:131], v[154:155]
	v_pk_mul_f32 v[156:157], v[132:133], v[156:157]
	global_store_dwordx4 v[174:175], v[154:157], off offset:128
	v_mul_f32_e32 v158, v102, v170
	v_mul_f32_e32 v159, v103, v170
	v_mul_f32_e32 v160, v104, v170
	v_mul_f32_e32 v161, v105, v170
	v_pk_mul_f32 v[158:159], v[134:135], v[158:159]
	v_pk_mul_f32 v[160:161], v[136:137], v[160:161]
	global_store_dwordx4 v[174:175], v[158:161], off offset:160
	v_mul_f32_e32 v154, v66, v171
	v_mul_f32_e32 v155, v67, v171
	v_mul_f32_e32 v156, v68, v171
	v_mul_f32_e32 v157, v69, v171
	v_pk_mul_f32 v[154:155], v[130:131], v[154:155]
	v_pk_mul_f32 v[156:157], v[132:133], v[156:157]
	global_store_dwordx4 v[176:177], v[154:157], off offset:128
	v_mul_f32_e32 v158, v70, v171
	v_mul_f32_e32 v159, v71, v171
	v_mul_f32_e32 v160, v72, v171
	v_mul_f32_e32 v161, v73, v171
	v_pk_mul_f32 v[158:159], v[134:135], v[158:159]
	v_pk_mul_f32 v[160:161], v[136:137], v[160:161]
	global_store_dwordx4 v[176:177], v[158:161], off offset:160
	v_mul_f32_e32 v154, v34, v172
	v_mul_f32_e32 v155, v35, v172
	v_mul_f32_e32 v156, v36, v172
	v_mul_f32_e32 v157, v37, v172
	v_pk_mul_f32 v[154:155], v[130:131], v[154:155]
	v_pk_mul_f32 v[156:157], v[132:133], v[156:157]
	global_store_dwordx4 v[178:179], v[154:157], off offset:128
	v_mul_f32_e32 v158, v38, v172
	v_mul_f32_e32 v159, v39, v172
	v_mul_f32_e32 v160, v40, v172
	v_mul_f32_e32 v161, v41, v172
	v_pk_mul_f32 v[158:159], v[134:135], v[158:159]
	v_pk_mul_f32 v[160:161], v[136:137], v[160:161]
	global_store_dwordx4 v[178:179], v[158:161], off offset:160
	v_mul_f32_e32 v154, v2, v173
	v_mul_f32_e32 v155, v3, v173
	v_mul_f32_e32 v156, v4, v173
	v_mul_f32_e32 v157, v5, v173
	v_pk_mul_f32 v[154:155], v[130:131], v[154:155]
	v_pk_mul_f32 v[156:157], v[132:133], v[156:157]
	global_store_dwordx4 v[180:181], v[154:157], off offset:128
	v_mul_f32_e32 v158, v6, v173
	v_mul_f32_e32 v159, v7, v173
	v_mul_f32_e32 v160, v8, v173
	v_mul_f32_e32 v161, v9, v173
	v_pk_mul_f32 v[158:159], v[134:135], v[158:159]
	v_pk_mul_f32 v[160:161], v[136:137], v[160:161]
	global_store_dwordx4 v[180:181], v[158:161], off offset:160
	global_load_dwordx4 v[130:133], v[182:183], off offset:192
	global_load_dwordx4 v[134:137], v[182:183], off offset:224
	s_waitcnt vmcnt(0)
	v_mul_f32_e32 v154, v106, v170
	v_mul_f32_e32 v155, v107, v170
	v_mul_f32_e32 v156, v108, v170
	v_mul_f32_e32 v157, v109, v170
	v_pk_mul_f32 v[154:155], v[130:131], v[154:155]
	v_pk_mul_f32 v[156:157], v[132:133], v[156:157]
	global_store_dwordx4 v[174:175], v[154:157], off offset:192
	v_mul_f32_e32 v158, v110, v170
	v_mul_f32_e32 v159, v111, v170
	v_mul_f32_e32 v160, v112, v170
	v_mul_f32_e32 v161, v113, v170
	v_pk_mul_f32 v[158:159], v[134:135], v[158:159]
	v_pk_mul_f32 v[160:161], v[136:137], v[160:161]
	global_store_dwordx4 v[174:175], v[158:161], off offset:224
	v_mul_f32_e32 v154, v74, v171
	v_mul_f32_e32 v155, v75, v171
	v_mul_f32_e32 v156, v76, v171
	v_mul_f32_e32 v157, v77, v171
	v_pk_mul_f32 v[154:155], v[130:131], v[154:155]
	v_pk_mul_f32 v[156:157], v[132:133], v[156:157]
	global_store_dwordx4 v[176:177], v[154:157], off offset:192
	v_mul_f32_e32 v158, v78, v171
	v_mul_f32_e32 v159, v79, v171
	v_mul_f32_e32 v160, v80, v171
	v_mul_f32_e32 v161, v81, v171
	v_pk_mul_f32 v[158:159], v[134:135], v[158:159]
	v_pk_mul_f32 v[160:161], v[136:137], v[160:161]
	global_store_dwordx4 v[176:177], v[158:161], off offset:224
	v_mul_f32_e32 v154, v42, v172
	v_mul_f32_e32 v155, v43, v172
	v_mul_f32_e32 v156, v44, v172
	v_mul_f32_e32 v157, v45, v172
	v_pk_mul_f32 v[154:155], v[130:131], v[154:155]
	v_pk_mul_f32 v[156:157], v[132:133], v[156:157]
	global_store_dwordx4 v[178:179], v[154:157], off offset:192
	v_mul_f32_e32 v158, v46, v172
	v_mul_f32_e32 v159, v47, v172
	v_mul_f32_e32 v160, v48, v172
	v_mul_f32_e32 v161, v49, v172
	v_pk_mul_f32 v[158:159], v[134:135], v[158:159]
	v_pk_mul_f32 v[160:161], v[136:137], v[160:161]
	global_store_dwordx4 v[178:179], v[158:161], off offset:224
	v_mul_f32_e32 v154, v10, v173
	v_mul_f32_e32 v155, v11, v173
	v_mul_f32_e32 v156, v12, v173
	v_mul_f32_e32 v157, v13, v173
	v_pk_mul_f32 v[154:155], v[130:131], v[154:155]
	v_pk_mul_f32 v[156:157], v[132:133], v[156:157]
	global_store_dwordx4 v[180:181], v[154:157], off offset:192
	v_mul_f32_e32 v158, v14, v173
	v_mul_f32_e32 v159, v15, v173
	v_mul_f32_e32 v160, v16, v173
	v_mul_f32_e32 v161, v17, v173
	v_pk_mul_f32 v[158:159], v[134:135], v[158:159]
	v_pk_mul_f32 v[160:161], v[136:137], v[160:161]
	global_store_dwordx4 v[180:181], v[158:161], off offset:224
	s_mov_b64 exec, -1
	s_branch .LBB0_1306
	s_waitcnt vmcnt(1)
	v_add_u32_e32 v130, s20, v197
	v_or_b32_e32 v178, v130, v194
	v_add_u32_e32 v130, 0xffffe000, v130
	s_waitcnt vmcnt(0)
	v_or_b32_e32 v158, s95, v201
	s_movk_i32 s10, 0x1fff
	v_ashrrev_i32_e32 v179, 31, v178
	v_lshrrev_b32_e32 v169, 11, v130
	v_cmp_lt_i32_e32 vcc, s10, v178
	v_lshlrev_b64 v[130:131], 12, v[178:179]
	v_ashrrev_i32_e32 v159, 31, v158
	v_cndmask_b32_e32 v185, 4, v169, vcc
	v_lshl_add_u64 v[130:131], s[54:55], 0, v[130:131]
	v_mov_b64_e32 v[132:133], s[62:63]
	s_movk_i32 s10, 0x6000
	v_lshlrev_b64 v[160:161], 2, v[158:159]
	v_mad_u64_u32 v[132:133], s[10:11], v185, s10, v[132:133]
	v_lshl_add_u64 v[174:175], v[130:131], 0, v[160:161]
	v_lshl_add_u64 v[162:163], v[132:133], 0, v[160:161]
	global_load_dwordx4 v[138:141], v[174:175], off
	global_load_dwordx4 v[134:137], v[174:175], off offset:32
	global_load_dwordx4 v[164:167], v[162:163], off
	global_load_dwordx4 v[154:157], v[162:163], off offset:32
	global_load_dwordx4 v[130:133], v[174:175], off offset:64
	global_load_dwordx4 v[142:145], v[174:175], off offset:96
	global_load_dwordx4 v[150:153], v[162:163], off offset:64
	global_load_dwordx4 v[146:149], v[162:163], off offset:96
	s_and_b64 vcc, exec, s[88:89]
	s_waitcnt vmcnt(5)
	v_pk_fma_f32 v[138:139], v[114:115], v[164:165], v[138:139]
	v_pk_fma_f32 v[140:141], v[116:117], v[166:167], v[140:141]
	s_cbranch_vccnz .LBB0_1520
	s_waitcnt vmcnt(4)
	v_pk_fma_f32 v[134:135], v[118:119], v[154:155], v[134:135]
	s_and_b64 vcc, exec, s[4:5]
	v_pk_fma_f32 v[136:137], v[120:121], v[156:157], v[136:137]
	s_cbranch_vccz .LBB0_1521

	.amdhsa_kernel _Z14fwd_megakernel6Params
		.amdhsa_group_segment_fixed_size 147472
		.amdhsa_private_segment_fixed_size 0
		.amdhsa_kernarg_size 1312
		.amdhsa_user_sgpr_count 2
		.amdhsa_user_sgpr_dispatch_ptr 0
		.amdhsa_user_sgpr_queue_ptr 0
		.amdhsa_user_sgpr_kernarg_segment_ptr 1
		.amdhsa_user_sgpr_dispatch_id 0
		.amdhsa_user_sgpr_kernarg_preload_length 0
		.amdhsa_user_sgpr_kernarg_preload_offset 0
		.amdhsa_user_sgpr_private_segment_size 0
		.amdhsa_uses_dynamic_stack 0
		.amdhsa_enable_private_segment 0
		.amdhsa_system_sgpr_workgroup_id_x 1
		.amdhsa_system_sgpr_workgroup_id_y 0
		.amdhsa_system_sgpr_workgroup_id_z 0
		.amdhsa_system_sgpr_workgroup_info 0
		.amdhsa_system_vgpr_workitem_id 2
		.amdhsa_next_free_vgpr 256
		.amdhsa_next_free_sgpr 102
		.amdhsa_accum_offset 256
		.amdhsa_reserve_vcc 1
		.amdhsa_float_round_mode_32 0
		.amdhsa_float_round_mode_16_64 0
		.amdhsa_float_denorm_mode_32 3
		.amdhsa_float_denorm_mode_16_64 3
		.amdhsa_dx10_clamp 1
		.amdhsa_ieee_mode 1
		.amdhsa_fp16_overflow 0
		.amdhsa_tg_split 0
		.amdhsa_exception_fp_ieee_invalid_op 0
		.amdhsa_exception_fp_denorm_src 0
		.amdhsa_exception_fp_ieee_div_zero 0
		.amdhsa_exception_fp_ieee_overflow 0
		.amdhsa_exception_fp_ieee_underflow 0
		.amdhsa_exception_fp_ieee_inexact 0
		.amdhsa_exception_int_div_zero 0
	.end_amdhsa_kernel

amdhsa.kernels:
  - .agpr_count:     0
    .args:
      - .offset:         0
        .size:           1056
        .value_kind:     by_value
      - .offset:         1056
        .size:           4
        .value_kind:     hidden_block_count_x
      - .offset:         1060
        .size:           4
        .value_kind:     hidden_block_count_y
      - .offset:         1064
        .size:           4
        .value_kind:     hidden_block_count_z
      - .offset:         1068
        .size:           2
        .value_kind:     hidden_group_size_x
      - .offset:         1070
        .size:           2
        .value_kind:     hidden_group_size_y
      - .offset:         1072
        .size:           2
        .value_kind:     hidden_group_size_z
      - .offset:         1074
        .size:           2
        .value_kind:     hidden_remainder_x
      - .offset:         1076
        .size:           2
        .value_kind:     hidden_remainder_y
      - .offset:         1078
        .size:           2
        .value_kind:     hidden_remainder_z
      - .offset:         1096
        .size:           8
        .value_kind:     hidden_global_offset_x
      - .offset:         1104
        .size:           8
        .value_kind:     hidden_global_offset_y
      - .offset:         1112
        .size:           8
        .value_kind:     hidden_global_offset_z
      - .offset:         1120
        .size:           2
        .value_kind:     hidden_grid_dims
      - .offset:         1144
        .size:           8
        .value_kind:     hidden_multigrid_sync_arg
    .group_segment_fixed_size: 147472
    .kernarg_segment_align: 8
    .kernarg_segment_size: 1312
    .language:       OpenCL C
    .language_version:
      - 2
      - 0
    .max_flat_workgroup_size: 512
    .name:           _Z14fwd_megakernel6Params
    .private_segment_fixed_size: 0
    .sgpr_count:     108
    .sgpr_spill_count: 81
    .symbol:         _Z14fwd_megakernel6Params.kd
    .uniform_work_group_size: 1
    .uses_dynamic_stack: false
    .vgpr_count:     256
    .vgpr_spill_count: 0
    .wavefront_size: 64
